# k9: k7 + side-unit prologue loads de-serialised (gain/normaliser loads issued with the row loads, waited where consumed)
# speedup vs baseline: 1.0076x; 1.0006x over previous
; template <int TYPE>
; __device__ __forceinline__ void mix_sg_unit(Frame& F, int b, int h, int mode  , const float* rot) {
;     ...
;     if (tid < 128) GN[tid] = (TYPE == 0 ? F.in[13] : F.in[14])[128 * h + tid];
.LBB0_729:
	s_lshl_b32 s59, s58, 7
	s_and_saveexec_b64 s[34:35], s[38:39]
	s_cbranch_execz .LBB0_731
	v_add_u32_e32 v4, s59, v145
	v_readlane_b32 s4, v252, 37
	v_ashrrev_i32_e32 v5, 31, v4
	v_readlane_b32 s16, v252, 49
	v_readlane_b32 s17, v252, 50
	v_readlane_b32 s5, v252, 38
	v_readlane_b32 s6, v252, 39
	v_lshl_add_u64 v[4:5], v[4:5], 2, s[16:17]
	global_load_dword v128, v[4:5], off
	v_readlane_b32 s7, v252, 40
	v_readlane_b32 s8, v252, 41
	v_readlane_b32 s9, v252, 42
	v_readlane_b32 s10, v252, 43
	v_readlane_b32 s11, v252, 44
	v_readlane_b32 s12, v252, 45
	v_readlane_b32 s13, v252, 46
	v_readlane_b32 s14, v252, 47
	v_readlane_b32 s15, v252, 48
	v_readlane_b32 s18, v252, 51
	v_readlane_b32 s19, v252, 52

; #define LAS __attribute__((address_space(3)))
; template <int TYPE>
; __device__ __forceinline__ void mix_sg_unit(Frame& F, int b, int h, int mode  , const float* rot) {
;     ...
;     if (tid < 128) GN[tid] = (TYPE == 0 ? F.in[13] : F.in[14])[128 * h + tid];
;     ...
;             *(LAS u32x4*)(L + MX_V + tk * MX_PITCH + 32 * p) = pa[4]; *(LAS u32x4*)(L + MX_V + tk * MX_PITCH + 32 * p + 16) = pa[5];
;             {
;                 const int c0 = (MX_POS4(16 * p)) * 2;
; #pragma unroll
;                 for (int g = 0; g < 4; ++g) {
;                     *(LAS u32x2*)(L + MX_Q + tk * MX_PITCH + c0 + 16 * g) = (u32x2){pa[g >> 1][2 * (g & 1)], pa[g >> 1][2 * (g & 1) + 1]};
;                     *(LAS u32x2*)(L + MX_K + tk * MX_PITCH + c0 + 16 * g) = (u32x2){pa[2 + (g >> 1)][2 * (g & 1)], pa[2 + (g >> 1)][2 * (g & 1) + 1]};
;                 }
;             }
;         }
;         if (w == 0) {
;             const bool valid = lane < ntok;
;             float li = -1e30f, lf = 0.f;
;             if (TYPE == 0) { if (valid) { li = pli + bias_i; lf = logsigmoidf_(plf + bias_f); } } else { if (valid) { li = 0.f; lf = lgam; } }
;             const float bb = row_prefix_sum(lf);
;             const float y = li - bb;
;             const float am = row_prefix_max(y);
;             const float a = bb + am;
;             const float B0 = rdlane(bb, 15), B1 = rdlane(bb, 31), B2 = rdlane(bb, 47), B3 = rdlane(bb, 63);
;             float M1 = 0.f, M2 = 0.f, M3 = 0.f, M4 = 0.f;
;             if (TYPE == 0) { const float A0 = rdlane(a, 15), A1 = rdlane(a, 31), A2 = rdlane(a, 47), A3 = rdlane(a, 63);
;                 M1 = fmaxf(B0 + m0, A0); M2 = fmaxf(B1 + M1, A1); M3 = fmaxf(B2 + M2, A2); M4 = fmaxf(B3 + M3, A3); }
;             const float m0q = q == 0 ? m0 : q == 1 ? M1 : q == 2 ? M2 : M3;
;             const float mnq = q == 0 ? M1 : q == 1 ? M2 : q == 2 ? M3 : M4;
;             const float b15 = q == 0 ? B0 : q == 1 ? B1 : q == 2 ? B2 : B3;
;             const float m = (TYPE == 0) ? fmaxf(bb + m0q, a) : 0.f;
;             SC[lane] = bb - m; SC[64 + lane] = y + LNKS; SC[128 + lane] = __expf(bb + m0q - m);
;             SC[192 + lane] = __expf(y + LNKS + b15 - mnq); SC[256 + lane] = __expf(-m);
;             if (r16 == 0) SC[320 + q] = __expf(b15 + m0q - mnq);
;             m0 = (nmc == 4) ? M4 : M1;
;         }
.Lsur_loaded:
	s_and_saveexec_b64 s[34:35], s[38:39]
	s_cbranch_execz .Lsur_gn
	s_waitcnt vmcnt(38)
	ds_write_b32 v87, v128
.Lsur_gn:
	s_or_b64 exec, exec, s[34:35]
	v_add_u32_e32 v2, v91, v66
	v_readlane_b32 s7, v254, 25
	s_and_b64 s[34:35], s[0:1], exec
	s_mov_b32 s7, s11
	s_cselect_b32 s60, 16, 8
	s_andn2_b64 vcc, exec, s[50:51]
	v_readlane_b32 s5, v254, 23
	s_waitcnt vmcnt(33)
	ds_write_b128 v2, v[52:55] offset:52224
	s_waitcnt vmcnt(32)
	ds_write_b128 v2, v[56:59] offset:52240
	v_add_u32_e32 v2, v91, v92
	ds_write2_b64 v2, v[4:5], v[6:7] offset1:2
	v_add_u32_e32 v4, 0x4000, v2
	ds_write2_b64 v4, v[44:45], v[46:47] offset0:128 offset1:130
	ds_write2_b64 v2, v[8:9], v[10:11] offset0:4 offset1:6
	ds_write2_b64 v4, v[48:49], v[50:51] offset0:132 offset1:134
	s_cbranch_vccnz .LBB0_735
	v_cmp_gt_u32_e32 vcc, s60, v190
	s_nop 1
	v_cndmask_b32_e32 v0, 0, v0, vcc
	v_cndmask_b32_e64 v2, v219, 0, vcc
	s_nop 0
	v_add_f32_dpp v0, v0, v0 row_shr:1 row_mask:0xf bank_mask:0xf bound_ctrl:1
	s_nop 1
	v_add_f32_dpp v0, v0, v0 row_shr:2 row_mask:0xf bank_mask:0xf bound_ctrl:1
	s_nop 1
	v_add_f32_dpp v0, v0, v0 row_shr:4 row_mask:0xf bank_mask:0xf bound_ctrl:1
	s_nop 1
	v_add_f32_dpp v4, v0, v0 row_shr:8 row_mask:0xf bank_mask:0xf bound_ctrl:1
	v_sub_f32_e32 v2, v2, v4
	v_readlane_b32 s36, v4, 47
	v_readlane_b32 s37, v4, 63
	v_readlane_b32 s35, v4, 31
	v_mov_b32_e32 v5, s36
	v_mov_b32_e32 v0, s37
	v_readlane_b32 s34, v4, 15
	v_cndmask_b32_e64 v0, v0, v5, s[84:85]
	v_mov_b32_e32 v5, s35
	v_cndmask_b32_e64 v0, v0, v5, s[96:97]
	v_mov_b32_e32 v5, s34
	v_cndmask_b32_e64 v0, v0, v5, s[20:21]
	v_add_f32_e32 v2, 0xc01b43d5, v2
	ds_write2st64_b32 v104, v4, v2 offset1:1
	v_add_f32_e32 v4, 0, v4
	v_add_f32_e32 v2, v2, v0
	v_mul_f32_e32 v4, 0x3fb8aa3b, v4
	v_mul_f32_e32 v2, 0x3fb8aa3b, v2
	v_exp_f32_e32 v4, v4
	v_exp_f32_e32 v2, v2
	ds_write2st64_b32 v104, v4, v2 offset0:2 offset1:3
	ds_write_b32 v104, v212 offset:1024
	s_and_saveexec_b64 s[34:35], s[72:73]
	s_cbranch_execz .LBB0_734
	v_add_f32_e32 v0, 0, v0
	v_mul_f32_e32 v0, 0x3fb8aa3b, v0
	v_exp_f32_e32 v0, v0
	ds_write_b32 v105, v0 offset:1280

; template <int TYPE>
; __device__ __forceinline__ void mix_sg_unit(Frame& F, int b, int h, int mode  , const float* rot) {
;     ...
;         if (TYPE == 0) {
; #pragma unroll
;             for (int r = 0; r < 4; ++r) nacc[r] = F.in[3][(size_t)(b * 4 + h) * 128 + 16 * w + 4 * q + r];
;             m0 = F.in[4][b * 4 + h];
;         }
.LBB0_742:
	s_and_b64 vcc, exec, s[28:29]
	s_cbranch_vccnz .LBB0_744
	s_lshl_b32 s76, s56, 9
	v_lshl_add_u64 v[0:1], v[68:69], 0, s[76:77]
	s_lshl_b32 s34, s56, 2
	v_readlane_b32 s4, v251, 5
	global_load_dwordx4 v[4:7], v[0:1], off
	v_mov_b32_e32 v0, s34
	v_readlane_b32 s12, v251, 13
	v_readlane_b32 s13, v251, 14
	v_readlane_b32 s5, v251, 6
	v_readlane_b32 s6, v251, 7
	v_readlane_b32 s7, v251, 8
	v_readlane_b32 s8, v251, 9
	v_readlane_b32 s9, v251, 10
	global_load_dword v0, v0, s[12:13]
	v_readlane_b32 s10, v251, 11
	v_readlane_b32 s11, v251, 12
	v_readlane_b32 s14, v251, 15
	v_readlane_b32 s15, v251, 16
	v_readlane_b32 s16, v251, 17
	v_readlane_b32 s17, v251, 18
	v_readlane_b32 s18, v251, 19
	v_readlane_b32 s19, v251, 20
	s_branch .LBB0_745

; #define LAS __attribute__((address_space(3)))
; template <int TYPE>
; __device__ __forceinline__ void mix_sg_unit(Frame& F, int b, int h, int mode  , const float* rot) {
;     ...
;     const float bias_i = (TYPE == 0) ? F.in[11][h] : 0.f, bias_f = (TYPE == 0) ? F.in[12][h] : 0.f;
;     LAS float* GN = (LAS float*)(L + MX_GN);
;     if (tid < 128) GN[tid] = (TYPE == 0 ? F.in[13] : F.in[14])[128 * h + tid];
.LBB0_745:
	s_and_b32 s34, s43, 3
	s_lshl_b32 s76, s34, 2
	v_readlane_b32 s4, v252, 37
	v_mov_b32_e32 v1, s76
	v_readlane_b32 s10, v252, 43
	v_readlane_b32 s11, v252, 44
	v_readlane_b32 s12, v252, 45
	v_readlane_b32 s13, v252, 46
	s_nop 2
	global_load_dword v34, v1, s[10:11]
	s_nop 0
	global_load_dword v35, v1, s[12:13]
	s_lshl_b32 s57, s34, 7
	v_readlane_b32 s5, v252, 38
	v_readlane_b32 s6, v252, 39
	v_readlane_b32 s7, v252, 40
	v_readlane_b32 s8, v252, 41
	v_readlane_b32 s9, v252, 42
	v_readlane_b32 s14, v252, 47
	v_readlane_b32 s15, v252, 48
	v_readlane_b32 s16, v252, 49
	v_readlane_b32 s17, v252, 50
	v_readlane_b32 s18, v252, 51
	v_readlane_b32 s19, v252, 52
	s_and_saveexec_b64 s[34:35], s[38:39]
	s_cbranch_execz .LBB0_747
	v_add_u32_e32 v8, s57, v145
	v_readlane_b32 s4, v252, 37
	v_ashrrev_i32_e32 v9, 31, v8
	v_readlane_b32 s14, v252, 47
	v_readlane_b32 s15, v252, 48
	v_readlane_b32 s5, v252, 38
	v_readlane_b32 s6, v252, 39
	v_lshl_add_u64 v[8:9], v[8:9], 2, s[14:15]
	global_load_dword v128, v[8:9], off
	v_readlane_b32 s7, v252, 40
	v_readlane_b32 s8, v252, 41
	v_readlane_b32 s9, v252, 42
	v_readlane_b32 s10, v252, 43
	v_readlane_b32 s11, v252, 44
	v_readlane_b32 s12, v252, 45
	v_readlane_b32 s13, v252, 46
	v_readlane_b32 s16, v252, 49
	v_readlane_b32 s17, v252, 50
	v_readlane_b32 s18, v252, 51
	v_readlane_b32 s19, v252, 52

; #define LAS __attribute__((address_space(3)))
; template <int TYPE>
; __device__ __forceinline__ void mix_sg_unit(Frame& F, int b, int h, int mode  , const float* rot) {
;     ...
;     if (tid < 128) GN[tid] = (TYPE == 0 ? F.in[13] : F.in[14])[128 * h + tid];
;     ...
;             *(LAS u32x4*)(L + MX_V + tk * MX_PITCH + 32 * p) = pa[4]; *(LAS u32x4*)(L + MX_V + tk * MX_PITCH + 32 * p + 16) = pa[5];
;             {
;                 const int c0 = (MX_POS4(16 * p)) * 2;
; #pragma unroll
;                 for (int g = 0; g < 4; ++g) {
;                     *(LAS u32x2*)(L + MX_Q + tk * MX_PITCH + c0 + 16 * g) = (u32x2){pa[g >> 1][2 * (g & 1)], pa[g >> 1][2 * (g & 1) + 1]};
;                     *(LAS u32x2*)(L + MX_K + tk * MX_PITCH + c0 + 16 * g) = (u32x2){pa[2 + (g >> 1)][2 * (g & 1)], pa[2 + (g >> 1)][2 * (g & 1) + 1]};
;                 }
;             }
;         }
;         if (w == 0) {
;             const bool valid = lane < ntok;
;             float li = -1e30f, lf = 0.f;
;             if (TYPE == 0) { if (valid) { li = pli + bias_i; lf = logsigmoidf_(plf + bias_f); } } else { if (valid) { li = 0.f; lf = lgam; } }
;             const float bb = row_prefix_sum(lf);
;             const float y = li - bb;
;             const float am = row_prefix_max(y);
;             const float a = bb + am;
;             const float B0 = rdlane(bb, 15), B1 = rdlane(bb, 31), B2 = rdlane(bb, 47), B3 = rdlane(bb, 63);
;             float M1 = 0.f, M2 = 0.f, M3 = 0.f, M4 = 0.f;
;             if (TYPE == 0) { const float A0 = rdlane(a, 15), A1 = rdlane(a, 31), A2 = rdlane(a, 47), A3 = rdlane(a, 63);
;                 M1 = fmaxf(B0 + m0, A0); M2 = fmaxf(B1 + M1, A1); M3 = fmaxf(B2 + M2, A2); M4 = fmaxf(B3 + M3, A3); }
;             const float m0q = q == 0 ? m0 : q == 1 ? M1 : q == 2 ? M2 : M3;
;             const float mnq = q == 0 ? M1 : q == 1 ? M2 : q == 2 ? M3 : M4;
;             const float b15 = q == 0 ? B0 : q == 1 ? B1 : q == 2 ? B2 : B3;
;             const float m = (TYPE == 0) ? fmaxf(bb + m0q, a) : 0.f;
;             SC[lane] = bb - m; SC[64 + lane] = y + LNKS; SC[128 + lane] = __expf(bb + m0q - m);
;             SC[192 + lane] = __expf(y + LNKS + b15 - mnq); SC[256 + lane] = __expf(-m);
;             if (r16 == 0) SC[320 + q] = __expf(b15 + m0q - mnq);
;             m0 = (nmc == 4) ? M4 : M1;
;         }
.Lsum_loaded:
	s_and_saveexec_b64 s[98:99], s[38:39]
	s_cbranch_execz .Lsum_gn
	s_waitcnt vmcnt(38)
	ds_write_b32 v87, v128
.Lsum_gn:
	s_or_b64 exec, exec, s[98:99]
	v_add_u32_e32 v37, v91, v66
	s_waitcnt vmcnt(33)
	ds_write_b128 v37, v[26:29] offset:52224
	s_waitcnt vmcnt(32)
	v_cvt_pk_bf16_f32 v16, v4, v5
	v_cvt_pk_bf16_f32 v17, v6, v7
	ds_write_b128 v37, v[30:33] offset:52240
	v_add_u32_e32 v26, v91, v92
	ds_write2_b64 v26, v[18:19], v[20:21] offset1:2
	v_add_u32_e32 v18, 0x4000, v26
	s_and_b64 vcc, exec, s[0:1]
	v_mov_b32_e32 v116, v0
	ds_write2_b64 v18, v[22:23], v[24:25] offset0:128 offset1:130
	ds_write2_b64 v26, v[8:9], v[10:11] offset0:4 offset1:6
	ds_write2_b64 v18, v[12:13], v[14:15] offset0:132 offset1:134
	s_cbranch_vccnz .LBB0_753
	v_add_f32_e32 v8, v35, v36
	s_mov_b32 s0, 0xbfb8aa3b
	v_mul_f32_e64 v9, |v8|, s0
	v_exp_f32_e32 v9, v9
	s_mov_b32 s0, 0x3f317217
	v_min_f32_e32 v8, 0, v8
	v_add_f32_e32 v2, v34, v2
	v_add_f32_e32 v9, 1.0, v9
	v_cmp_gt_f32_e32 vcc, s81, v9
	s_nop 1
	v_cndmask_b32_e64 v10, 0, 32, vcc
	v_ldexp_f32 v9, v9, v10
	v_log_f32_e32 v9, v9
	v_cndmask_b32_e32 v10, 0, v220, vcc
	v_mul_f32_e32 v11, 0x3f317217, v9
	v_fma_f32 v11, v9, s0, -v11
	v_fmac_f32_e32 v11, 0x3377d1cf, v9
	s_mov_b32 s0, 0x7f800000
	v_fmac_f32_e32 v11, 0x3f317217, v9
	v_cmp_lt_f32_e64 vcc, |v9|, s0
	s_nop 1
	v_cndmask_b32_e32 v9, v9, v11, vcc
	v_sub_f32_e32 v9, v9, v10
	v_sub_f32_e32 v8, v8, v9
	v_cmp_gt_u32_e32 vcc, s59, v190
	s_nop 1
	v_cndmask_b32_e32 v8, 0, v8, vcc
	v_cndmask_b32_e32 v2, v219, v2, vcc
	s_nop 0
	v_add_f32_dpp v8, v8, v8 row_shr:1 row_mask:0xf bank_mask:0xf bound_ctrl:1
	s_nop 1
	v_add_f32_dpp v8, v8, v8 row_shr:2 row_mask:0xf bank_mask:0xf bound_ctrl:1
	s_nop 1
	v_add_f32_dpp v8, v8, v8 row_shr:4 row_mask:0xf bank_mask:0xf bound_ctrl:1
	s_nop 1
	v_add_f32_dpp v9, v8, v8 row_shr:8 row_mask:0xf bank_mask:0xf bound_ctrl:1
	v_sub_f32_e32 v10, v2, v9
	v_mov_b32_e32 v2, 0xff61b1e6
	v_mov_b32_e32 v8, 0xff61b1e6
	v_readlane_b32 s0, v9, 15
	v_mov_b32_dpp v2, v10 row_shr:1 row_mask:0xf bank_mask:0xf
	v_max_f32_e32 v2, v2, v2
	v_max_f32_e32 v2, v10, v2
	v_readlane_b32 s1, v9, 31
	v_readlane_b32 s34, v9, 47
	v_mov_b32_dpp v8, v2 row_shr:2 row_mask:0xf bank_mask:0xf
	v_max_f32_e32 v8, v8, v8
	v_max_f32_e32 v2, v2, v8
	v_mov_b32_e32 v8, 0xff61b1e6
	v_readlane_b32 s35, v9, 63
	v_add_f32_e32 v10, 0xc01b43d5, v10
	v_mov_b32_dpp v8, v2 row_shr:4 row_mask:0xf bank_mask:0xf
	v_max_f32_e32 v8, v8, v8
	v_max_f32_e32 v2, v2, v8
	v_mov_b32_e32 v8, 0xff61b1e6
	s_nop 1
	v_mov_b32_dpp v8, v2 row_shr:8 row_mask:0xf bank_mask:0xf
	v_max_f32_e32 v8, v8, v8
	v_max_f32_e32 v2, v2, v8
	v_add_f32_e32 v11, v9, v2
	v_add_f32_e32 v2, s0, v0
	v_readlane_b32 s60, v11, 15
	v_readlane_b32 s61, v11, 31
	v_readlane_b32 s62, v11, 47
	v_max_f32_e64 v8, s60, s60
	v_max_f32_e32 v116, v2, v8
	v_add_f32_e32 v2, s1, v116
	v_max_f32_e64 v8, s61, s61
	v_max_f32_e32 v2, v2, v8
	v_add_f32_e32 v8, s34, v2
	v_max_f32_e64 v12, s62, s62
	v_readlane_b32 s63, v11, 63
	v_max_f32_e32 v8, v8, v12
	v_add_f32_e32 v12, s35, v8
	v_max_f32_e64 v13, s63, s63
	v_max_f32_e32 v12, v12, v13
	v_cndmask_b32_e64 v13, v8, v2, s[84:85]
	v_cndmask_b32_e64 v8, v12, v8, s[84:85]
	v_cndmask_b32_e64 v2, v8, v2, s[96:97]
	v_mov_b32_e32 v8, s35
	v_mov_b32_e32 v12, s34
	v_cndmask_b32_e64 v13, v13, v116, s[96:97]
	v_cndmask_b32_e64 v8, v8, v12, s[84:85]
	v_mov_b32_e32 v12, s1
	v_cndmask_b32_e64 v0, v13, v0, s[20:21]
	v_cndmask_b32_e64 v8, v8, v12, s[96:97]
	v_mov_b32_e32 v12, s0
	v_cndmask_b32_e64 v8, v8, v12, s[20:21]
	v_add_f32_e32 v12, v9, v0
	v_cndmask_b32_e64 v2, v2, v116, s[20:21]
	v_max_f32_e32 v11, v12, v11
	v_add_f32_e32 v13, v10, v8
	v_sub_f32_e32 v12, v12, v11
	v_sub_f32_e32 v13, v13, v2
	v_mul_f32_e32 v12, 0x3fb8aa3b, v12
	v_mul_f32_e32 v13, 0x3fb8aa3b, v13
	v_exp_f32_e32 v12, v12
	v_exp_f32_e32 v13, v13
	v_mul_f32_e32 v14, 0xbfb8aa3b, v11
	v_exp_f32_e32 v14, v14
	v_sub_f32_e32 v9, v9, v11
	ds_write2st64_b32 v104, v9, v10 offset1:1
	ds_write2st64_b32 v104, v12, v13 offset0:2 offset1:3
	ds_write_b32 v104, v14 offset:1024
	s_and_saveexec_b64 s[0:1], s[72:73]
	s_cbranch_execz .LBB0_752
	v_add_f32_e32 v0, v8, v0
	v_sub_f32_e32 v0, v0, v2
	v_mul_f32_e32 v0, 0x3fb8aa3b, v0
	v_exp_f32_e32 v0, v0
	ds_write_b32 v105, v0 offset:1280

; __device__ __forceinline__ void mix_hg_unit(Frame& F, int b, int h, int mode) {
;     ...
;     if (tid < 128) GN[tid] = F.in[18][128 * h + tid];
.LBB0_863:
	s_and_b64 vcc, exec, s[28:29]
	s_cbranch_vccz .LBB0_852
	s_ashr_i32 s25, s24, 31
	s_lshl_b64 s[28:29], s[24:25], 16
	s_add_i32 s25, s26, 0x20000
	s_and_b32 s76, s25, 0x380
	s_and_saveexec_b64 s[34:35], s[4:5]
	s_cbranch_execz .LBB0_866
	v_add_u32_e32 v0, s76, v145
	v_readlane_b32 s56, v252, 13
	v_ashrrev_i32_e32 v1, 31, v0
	v_readlane_b32 s60, v252, 17
	v_readlane_b32 s61, v252, 18
	v_readlane_b32 s62, v252, 19
	v_readlane_b32 s63, v252, 20
	v_lshl_add_u64 v[0:1], v[0:1], 2, s[60:61]
	global_load_dword v158, v[0:1], off
	v_readlane_b32 s64, v252, 21
	v_readlane_b32 s65, v252, 22
	v_readlane_b32 s66, v252, 23
	v_readlane_b32 s67, v252, 24
	v_readlane_b32 s71, v252, 28
	v_readlane_b32 s62, v253, 29
	v_readlane_b32 s64, v252, 3
	s_mov_b32 s71, s43
	v_readlane_b32 s63, v253, 30
	v_readlane_b32 s65, v252, 4
	v_readlane_b32 s66, v254, 30
	v_readlane_b32 s57, v252, 14
	v_readlane_b32 s58, v252, 15
	v_readlane_b32 s59, v252, 16
	v_readlane_b32 s68, v252, 25
	v_readlane_b32 s69, v252, 26
	v_readlane_b32 s70, v252, 27
	v_readlane_b32 s67, v254, 31

; #define LAS __attribute__((address_space(3)))
; __device__ __forceinline__ void mix_hg_unit(Frame& F, int b, int h, int mode) {
;     ...
;     if (!prompt) {
;         const float* Sin = F.in[6] + (size_t)(b * 8 + h) * 16384;
; #pragma unroll
;         for (int mt = 0; mt < 8; ++mt)
; #pragma unroll
;             for (int r = 0; r < 4; ++r) S[mt][r] = __builtin_nontemporal_load(Sin + (16 * mt + 4 * q + r) * 128 + 16 * w + r16);
;     }
;     LAS float* GN = (LAS float*)(L + MX_GN);
;     if (tid < 128) GN[tid] = F.in[18][128 * h + tid];
.LBB0_870:
	s_or_b64 exec, exec, s[36:37]
	s_lshl_b32 s98, s24, 16
	s_mov_b32 s99, 0
	v_lshl_add_u64 v[142:143], v[100:101], 0, s[98:99]
	s_mov_b32 s98, 0x2000
	global_load_dword v40, v[142:143], off nt
	global_load_dword v41, v[142:143], off offset:512 nt
	global_load_dword v42, v[142:143], off offset:1024 nt
	global_load_dword v43, v[142:143], off offset:1536 nt
	v_lshl_add_u64 v[142:143], v[142:143], 0, s[98:99]
	global_load_dword v44, v[142:143], off nt
	global_load_dword v45, v[142:143], off offset:512 nt
	global_load_dword v46, v[142:143], off offset:1024 nt
	global_load_dword v47, v[142:143], off offset:1536 nt
	v_lshl_add_u64 v[142:143], v[142:143], 0, s[98:99]
	global_load_dword v36, v[142:143], off nt
	global_load_dword v37, v[142:143], off offset:512 nt
	global_load_dword v38, v[142:143], off offset:1024 nt
	global_load_dword v39, v[142:143], off offset:1536 nt
	v_lshl_add_u64 v[142:143], v[142:143], 0, s[98:99]
	global_load_dword v32, v[142:143], off nt
	global_load_dword v33, v[142:143], off offset:512 nt
	global_load_dword v34, v[142:143], off offset:1024 nt
	global_load_dword v35, v[142:143], off offset:1536 nt
	v_lshl_add_u64 v[142:143], v[142:143], 0, s[98:99]
	global_load_dword v28, v[142:143], off nt
	global_load_dword v29, v[142:143], off offset:512 nt
	global_load_dword v30, v[142:143], off offset:1024 nt
	global_load_dword v31, v[142:143], off offset:1536 nt
	v_lshl_add_u64 v[142:143], v[142:143], 0, s[98:99]
	global_load_dword v20, v[142:143], off nt
	global_load_dword v21, v[142:143], off offset:512 nt
	global_load_dword v22, v[142:143], off offset:1024 nt
	global_load_dword v23, v[142:143], off offset:1536 nt
	v_lshl_add_u64 v[142:143], v[142:143], 0, s[98:99]
	global_load_dword v16, v[142:143], off nt
	global_load_dword v17, v[142:143], off offset:512 nt
	global_load_dword v18, v[142:143], off offset:1024 nt
	global_load_dword v19, v[142:143], off offset:1536 nt
	v_lshl_add_u64 v[142:143], v[142:143], 0, s[98:99]
	global_load_dword v12, v[142:143], off nt
	global_load_dword v13, v[142:143], off offset:512 nt
	global_load_dword v14, v[142:143], off offset:1024 nt
	global_load_dword v15, v[142:143], off offset:1536 nt
	v_add_u32_e32 v2, v108, v107
	s_and_saveexec_b64 s[98:99], s[4:5]
	s_cbranch_execz .Lsuh_gn
	s_waitcnt vmcnt(38)
	ds_write_b32 v104, v158
; template <int NMC>
; __device__ __forceinline__ void hg_chain(LAS unsigned char* L, f32x4 (&S)[8], int w, int r16, int q) {
;     ...
;     for (int mc = 0; mc < NMC; ++mc) {
;         oo[mc] = (f32x4){0.f, 0.f, 0.f, 0.f};
;         {
;             const LAS unsigned char* Qb = L + MX_Q + 16 * mc * MX_PITCH; const LAS unsigned char* Kb = L + MX_K + 16 * mc * MX_PITCH; const LAS unsigned char* Vb = L + MX_V + 16 * mc * MX_PITCH;
;             f32x4 g0 = {0.f, 0.f, 0.f, 0.f}, g1 = {0.f, 0.f, 0.f, 0.f};
; #pragma unroll
;             for (int ks = 0; ks < 4; ++ks) {
;                 const bf16x8 kf = ld8(Kb + r16 * MX_PITCH + (32 * ks + 8 * q) * 2), qf = ld8(Qb + r16 * MX_PITCH + (32 * ks + 8 * q) * 2);
;                 if (ks & 1) g1 = MFMA16(kf, qf, g1); else g0 = MFMA16(kf, qf, g0);
;             }
;             const f32x4 g = g0 + g1;
;             f32x4 P;
; #pragma unroll
; __device__ __forceinline__ void mix_hg_unit(Frame& F, int b, int h, int mode) {
;     ...
;         {
;             const int c0 = (MX_POS4(16 * p)) * 2;
; #pragma unroll
;             for (int g = 0; g < 4; ++g) {
;                 *(LAS u32x2*)(L + MX_Q + tk * MX_PITCH + c0 + 16 * g) = (u32x2){pa[g >> 1][2 * (g & 1)], pa[g >> 1][2 * (g & 1) + 1]};
;                 *(LAS u32x2*)(L + MX_K + tk * MX_PITCH + c0 + 16 * g) = (u32x2){pa[2 + (g >> 1)][2 * (g & 1)], pa[2 + (g >> 1)][2 * (g & 1) + 1]};
;             }
;             *(LAS u32x4*)(L + MX_V + tk * MX_PITCH + 32 * p) = pa[4]; *(LAS u32x4*)(L + MX_V + tk * MX_PITCH + 32 * p + 16) = pa[5];
;             GD[tid] = pgd;
;         }
;         MSTAMP(9);
;         __syncthreads();
;         MSTAMP(10);
;         if (sc + 1 < nsc) HG_LOAD(sc + 1);
;         { const __amdgpu_buffer_rsrc_t rz = Z_RSRC(ZROW(F, row0, 1), ntok); pg[0] = Z_LD(rz, zvo + 6144); pg[1] = Z_LD(rz, zvo + 6160); }
;         MSTAMP(11);
;         if (nmc == 4) hg_chain<4>(L, S, w, r16, q); else hg_chain<1>(L, S, w, r16, q);
;         MSTAMP(12);
;         __syncthreads();
;         MSTAMP(13);
;         {
;             const bool valid = tk < ntok; const int row = row0 + (valid ? tk : 0);
;             f32x4 o[4];
; #pragma unroll
;             for (int c = 0; c < 4; ++c) o[c] = *(const LAS f32x4*)(OB + tk * MX_OP + 16 * p + 4 * c);
;             if (tk >= 16 * nmc) {
; #pragma unroll
;                 for (int c = 0; c < 4; ++c) o[c] = (f32x4){0.f, 0.f, 0.f, 0.f}; }
.Lsuh_gn:
	s_or_b64 exec, exec, s[98:99]
	s_waitcnt vmcnt(37)
	ds_write2_b64 v2, v[48:49], v[50:51] offset1:2
	v_add_u32_e32 v48, 0x4000, v2
	s_mov_b64 s[56:57], s[68:69]
	s_waitcnt vmcnt(35)
	ds_write2_b64 v48, v[52:53], v[54:55] offset0:128 offset1:130
	ds_write2_b64 v2, v[4:5], v[6:7] offset0:4 offset1:6
	s_waitcnt vmcnt(34)
	ds_write2_b64 v48, v[8:9], v[10:11] offset0:132 offset1:134
	v_add_u32_e32 v2, v108, v94
	s_mov_b32 s58, s70
	s_mov_b32 s59, s71
	s_waitcnt vmcnt(33)
	ds_write_b128 v2, v[24:27] offset:52224
	s_waitcnt vmcnt(32)
	ds_write_b128 v2, v[56:59] offset:52240
	ds_write_b32 v109, v1
	s_waitcnt lgkmcnt(0)
	s_barrier
	buffer_load_dwordx4 v[8:11], v0, s[56:59], 0 offen offset:2048
	buffer_load_dwordx4 v[4:7], v0, s[56:59], 0 offen offset:2064
	v_add_u32_e32 v0, v95, v112
	ds_read_b128 v[24:27], v0
	ds_read_b128 v[48:51], v0 offset:17408
	ds_read_b128 v[52:55], v0 offset:64
	ds_read_b128 v[56:59], v0 offset:17472
	ds_read_b128 v[60:63], v0 offset:128
	ds_read_b128 v[64:67], v0 offset:17536
	ds_read_b128 v[76:79], v0 offset:192
	ds_read_b128 v[68:71], v0 offset:17600
	s_waitcnt lgkmcnt(6)
	v_mfma_f32_16x16x32_bf16 v[48:51], v[48:51], v[24:27], 0
	s_mov_b32 s50, s58
	v_writelane_b32 v254, s48, 22
	s_waitcnt lgkmcnt(4)
	v_mfma_f32_16x16x32_bf16 v[56:59], v[56:59], v[52:55], 0
	v_writelane_b32 v254, s49, 23
	v_writelane_b32 v254, s50, 24
	v_writelane_b32 v254, s51, 25
	s_waitcnt lgkmcnt(2)
	v_mfma_f32_16x16x32_bf16 v[48:51], v[64:67], v[60:63], v[48:51]
	s_waitcnt lgkmcnt(0)
	v_mfma_f32_16x16x32_bf16 v[56:59], v[68:71], v[76:79], v[56:59]
	v_mov_b32_e32 v70, v3
	v_mov_b32_e32 v71, v3
	s_nop 5
	v_pk_add_f32 v[0:1], v[50:51], v[58:59]
	v_pk_add_f32 v[48:49], v[48:49], v[56:57]
	v_cndmask_b32_e64 v1, v1, 0, s[10:11]
	v_cndmask_b32_e64 v2, v48, 0, s[16:17]
	v_cndmask_b32_e64 v48, 0, v49, s[14:15]
	v_cndmask_b32_e64 v49, v0, 0, s[12:13]
	v_add_u32_e32 v0, v117, v118
	ds_read_b64_tr_b16 v[68:69], v0 offset:52224
	v_cvt_pk_bf16_f32 v0, v2, v48
	v_cvt_pk_bf16_f32 v1, v49, v1
	v_mov_b32_e32 v2, v3
	s_waitcnt vmcnt(2)
	v_cvt_pk_bf16_f32 v56, v40, v41
	v_cvt_pk_bf16_f32 v57, v42, v43
	s_waitcnt lgkmcnt(0)
	v_mfma_f32_16x16x32_bf16 v[48:51], v[0:3], v[68:71], 0
	v_cvt_pk_bf16_f32 v58, v44, v45
	v_cvt_pk_bf16_f32 v59, v46, v47
	s_nop 1
	v_mfma_f32_16x16x32_bf16 v[24:27], v[24:27], v[56:59], v[48:51]
	v_mov_b32_e32 v58, v3
	v_mov_b32_e32 v59, v3
	s_nop 0
	v_cvt_pk_bf16_f32 v48, v36, v37
	v_cvt_pk_bf16_f32 v49, v38, v39
	v_cvt_pk_bf16_f32 v50, v32, v33
	v_cvt_pk_bf16_f32 v51, v34, v35
	s_nop 1
	v_mfma_f32_16x16x32_bf16 v[48:51], v[52:55], v[48:51], 0
	v_cvt_pk_bf16_f32 v52, v28, v29
	v_cvt_pk_bf16_f32 v53, v30, v31
	v_cvt_pk_bf16_f32 v54, v20, v21
	v_cvt_pk_bf16_f32 v55, v22, v23
	s_nop 1
	v_mfma_f32_16x16x32_bf16 v[72:75], v[60:63], v[52:55], v[24:27]
	s_nop 2
	v_cvt_pk_bf16_f32 v24, v16, v17
	v_cvt_pk_bf16_f32 v25, v18, v19
	v_cvt_pk_bf16_f32 v26, v12, v13
	v_cvt_pk_bf16_f32 v27, v14, v15
	s_nop 1
	v_mfma_f32_16x16x32_bf16 v[80:83], v[76:79], v[24:27], v[48:51]
	ds_read_b128 v[24:27], v119
	ds_read_b64_tr_b16 v[0:1], v123 offset:17408
	ds_read_b64_tr_b16 v[56:57], v123 offset:17416
	ds_read_b128 v[48:51], v119 offset:64
	s_waitcnt lgkmcnt(2)
	v_mfma_f32_16x16x32_bf16 v[52:55], v[0:3], v[68:71], v[40:43]
	s_nop 2
	ds_read_b128 v[40:43], v119 offset:128
	ds_read_b64_tr_b16 v[0:1], v123 offset:17472
	s_waitcnt lgkmcnt(3)
	v_mfma_f32_16x16x32_bf16 v[44:47], v[56:59], v[68:71], v[44:47]
	s_waitcnt lgkmcnt(0)
	v_mfma_f32_16x16x32_bf16 v[56:59], v[0:3], v[68:71], v[36:39]
	s_nop 2
	ds_read_b128 v[36:39], v119 offset:192
	ds_read_b64_tr_b16 v[0:1], v123 offset:17480
	s_waitcnt lgkmcnt(0)
	v_mfma_f32_16x16x32_bf16 v[60:63], v[0:3], v[68:71], v[32:35]
	s_nop 2
	ds_read_b128 v[32:35], v119 offset:256
	ds_read_b64_tr_b16 v[0:1], v123 offset:17536
	s_waitcnt lgkmcnt(0)
	v_mfma_f32_16x16x32_bf16 v[64:67], v[0:3], v[68:71], v[28:31]
	s_nop 2
	ds_read_b128 v[28:31], v119 offset:320
	ds_read_b64_tr_b16 v[0:1], v123 offset:17544
	s_waitcnt lgkmcnt(0)
	v_mfma_f32_16x16x32_bf16 v[76:79], v[0:3], v[68:71], v[20:23]
	s_nop 2
	ds_read_b128 v[20:23], v119 offset:384
	ds_read_b64_tr_b16 v[0:1], v124 offset:17408
	s_waitcnt lgkmcnt(0)
	v_mfma_f32_16x16x32_bf16 v[84:87], v[0:3], v[68:71], v[16:19]
	s_nop 2
	ds_read_b128 v[16:19], v119 offset:448
	ds_read_b64_tr_b16 v[0:1], v125 offset:17408
	s_waitcnt lgkmcnt(0)
	v_mfma_f32_16x16x32_bf16 v[12:15], v[0:3], v[68:71], v[12:15]
	v_add_f32_e64 v68, v72, v80
	v_add_f32_e64 v69, v73, v81
	v_add_u32_e32 v2, v113, v116
	v_pk_add_f32 v[0:1], v[74:75], v[82:83]
	ds_write2_b32 v2, v68, v69 offset1:132
	v_add_u32_e32 v2, v113, v115
	ds_write_b32 v2, v0
	v_add_u32_e32 v0, v113, v114
	ds_write_b32 v0, v1
	s_waitcnt lgkmcnt(0)
	s_barrier
	s_waitcnt vmcnt(0)
	ds_read_b128 v[88:91], v110
	ds_read_b128 v[80:83], v110 offset:16
	ds_read_b128 v[72:75], v110 offset:32
	ds_read_b128 v[68:71], v110 offset:48
	s_and_saveexec_b64 s[36:37], s[20:21]
	s_cbranch_execz .LBB0_872
	s_waitcnt lgkmcnt(2)
	v_mov_b32_e32 v80, 0
	v_mov_b32_e32 v81, v80
	v_mov_b32_e32 v82, v80
	v_mov_b32_e32 v83, v80
	v_mov_b32_e32 v88, v80
	v_mov_b32_e32 v89, v80
	v_mov_b32_e32 v90, v80
	v_mov_b32_e32 v91, v80
	s_waitcnt lgkmcnt(1)
	v_mov_b32_e32 v72, v80
	v_mov_b32_e32 v73, v80
	v_mov_b32_e32 v74, v80
	v_mov_b32_e32 v75, v80
	s_waitcnt lgkmcnt(0)
	v_mov_b32_e32 v68, v80
	v_mov_b32_e32 v69, v80
	v_mov_b32_e32 v70, v80
	v_mov_b32_e32 v71, v80
